# mix_out epilogue: all 12 gate loads issued up front (regs parked in free LDS), counted vmcnt instead of vmcnt(0) per step
# speedup vs baseline: 1.0078x; 1.0078x over previous
.LBB0_920:
	s_xor_b64 s[62:63], s[62:63], -1
	s_andn2_b64 vcc, exec, s[80:81]
	s_cbranch_vccnz .LBB0_855
	ds_read_b128 v[0:3], v187 offset:52224
	ds_read_b128 v[4:7], v150 offset:27648
	ds_read_b128 v[32:35], v187 offset:52256
	ds_read_b128 v[36:39], v150 offset:27680
	v_readlane_b32 s0, v254, 2
	v_readlane_b32 s1, v254, 3
	s_waitcnt lgkmcnt(2)
	v_mfma_f32_32x32x16_bf16 v[16:31], v[0:3], v[4:7], 0
	ds_read_b128 v[0:3], v188 offset:52224
	ds_read_b128 v[4:7], v152 offset:27648
	ds_read_b128 v[40:43], v187 offset:52288
	ds_read_b128 v[44:47], v150 offset:27712
	v_cmp_lt_i32_e32 vcc, v231, v230
	v_lshl_add_u64 v[182:183], s[84:85], 0, v[154:155]
	s_nop 0
	v_cndmask_b32_e32 v48, v229, v231, vcc
	s_mul_i32 vcc_lo, s16, 0x180
	s_waitcnt lgkmcnt(2)
	v_mfma_f32_32x32x16_bf16 v[0:15], v[0:3], v[4:7], 0
	v_mfma_f32_32x32x16_bf16 v[16:31], v[32:35], v[36:39], v[16:31]
	ds_read_b128 v[32:35], v188 offset:52256
	ds_read_b128 v[36:39], v152 offset:27680
	ds_read_b128 v[98:101], v188 offset:52288
	ds_read_b128 v[102:105], v152 offset:27712
	s_waitcnt lgkmcnt(2)
	v_mfma_f32_32x32x16_bf16 v[0:15], v[32:35], v[36:39], v[0:15]
	v_mfma_f32_32x32x16_bf16 v[16:31], v[40:43], v[44:47], v[16:31]
	s_waitcnt lgkmcnt(0)
	v_mfma_f32_32x32x16_bf16 v[0:15], v[98:101], v[102:105], v[0:15]
	s_nop 9
	v_cndmask_b32_e64 v16, v16, 0, s[0:1]
	v_readlane_b32 s0, v254, 4
	v_readlane_b32 s1, v254, 5
	v_cndmask_b32_e64 v0, v0, 0, s[18:19]
	s_nop 0
	v_cndmask_b32_e64 v1, v1, 0, s[0:1]
	v_readlane_b32 s0, v254, 6
	v_add_f32_e32 v16, v16, v0
	v_cndmask_b32_e64 v0, 0, v17, s[18:19]
	v_readlane_b32 s1, v254, 7
	v_add_f32_e32 v17, v0, v1
	s_nop 0
	v_cndmask_b32_e64 v1, v19, 0, s[0:1]
	v_readlane_b32 s0, v254, 8
	v_readlane_b32 s1, v254, 9
	s_nop 1
	v_cndmask_b32_e64 v0, v18, 0, s[0:1]
	v_readlane_b32 s0, v254, 10
	v_readlane_b32 s1, v254, 11
	s_nop 1
	v_cndmask_b32_e64 v3, v3, 0, s[0:1]
	v_readlane_b32 s0, v254, 12
	v_readlane_b32 s1, v254, 13
	s_nop 1
	v_cndmask_b32_e64 v2, v2, 0, s[0:1]
	v_readlane_b32 s0, v254, 14
	v_pk_add_f32 v[0:1], v[0:1], v[2:3]
	v_readlane_b32 s1, v254, 15
	v_cvt_pk_bf16_f32 v3, v0, v1
	v_cvt_pk_bf16_f32 v2, v16, v17
	v_cndmask_b32_e64 v1, v21, 0, s[0:1]
	v_readlane_b32 s0, v254, 16
	v_readlane_b32 s1, v254, 17
	s_nop 1
	v_cndmask_b32_e64 v0, v20, 0, s[0:1]
	v_readlane_b32 s0, v254, 23
	v_readlane_b32 s1, v254, 24
	s_nop 1
	v_cndmask_b32_e64 v5, v5, 0, s[0:1]
	v_readlane_b32 s0, v254, 25
	v_readlane_b32 s1, v254, 26
	s_nop 1
	v_cndmask_b32_e64 v4, v4, 0, s[0:1]
	v_readlane_b32 s0, v254, 27
	v_readlane_b32 s1, v254, 28
	v_pk_add_f32 v[0:1], v[0:1], v[4:5]
	s_nop 0
	v_cndmask_b32_e64 v5, v23, 0, s[0:1]
	v_readlane_b32 s0, v254, 29
	v_readlane_b32 s1, v254, 30
	v_cvt_pk_bf16_f32 v0, v0, v1
	s_nop 0
	v_cndmask_b32_e64 v4, v22, 0, s[0:1]
	v_readlane_b32 s0, v254, 31
	v_readlane_b32 s1, v254, 32
	s_nop 1
	v_cndmask_b32_e64 v7, v7, 0, s[0:1]
	v_readlane_b32 s0, v254, 33
	v_readlane_b32 s1, v254, 34
	s_nop 1
	v_cndmask_b32_e64 v6, v6, 0, s[0:1]
	v_pk_add_f32 v[4:5], v[4:5], v[6:7]
	v_readlane_b32 s0, v254, 35
	v_cvt_pk_bf16_f32 v1, v4, v5
	v_readlane_b32 s1, v254, 36
	ds_write2_b64 v151, v[2:3], v[0:1] offset1:2
	s_nop 0
	v_cndmask_b32_e64 v1, v25, 0, s[0:1]
	v_readlane_b32 s0, v254, 37
	v_readlane_b32 s1, v254, 38
	s_nop 1
	v_cndmask_b32_e64 v0, v24, 0, s[0:1]
	v_readlane_b32 s0, v254, 39
	v_readlane_b32 s1, v254, 40
	s_nop 1
	v_cndmask_b32_e64 v3, v9, 0, s[0:1]
	v_readlane_b32 s0, v254, 41
	v_readlane_b32 s1, v254, 42
	s_nop 1
	v_cndmask_b32_e64 v2, v8, 0, s[0:1]
	v_readlane_b32 s0, v254, 43
	v_readlane_b32 s1, v254, 44
	v_pk_add_f32 v[0:1], v[0:1], v[2:3]
	s_nop 0
	v_cndmask_b32_e64 v3, v27, 0, s[0:1]
	v_readlane_b32 s0, v254, 45
	v_readlane_b32 s1, v254, 46
	v_cvt_pk_bf16_f32 v0, v0, v1
	s_nop 0
	v_cndmask_b32_e64 v2, v26, 0, s[0:1]
	v_readlane_b32 s0, v254, 47
	v_readlane_b32 s1, v254, 48
	s_nop 1
	v_cndmask_b32_e64 v5, v11, 0, s[0:1]
	v_readlane_b32 s0, v254, 49
	v_readlane_b32 s1, v254, 50
	s_nop 1
	v_cndmask_b32_e64 v4, v10, 0, s[0:1]
	v_readlane_b32 s0, v254, 51
	v_pk_add_f32 v[2:3], v[2:3], v[4:5]
	v_readlane_b32 s1, v254, 52
	v_cvt_pk_bf16_f32 v1, v2, v3
	s_nop 0
	v_cndmask_b32_e64 v3, v29, 0, s[0:1]
	v_readlane_b32 s0, v254, 53
	v_readlane_b32 s1, v254, 54
	s_nop 1
	v_cndmask_b32_e64 v2, v28, 0, s[0:1]
	v_readlane_b32 s0, v254, 55
	v_readlane_b32 s1, v254, 56
	s_nop 1
	v_cndmask_b32_e64 v5, v13, 0, s[0:1]
	v_readlane_b32 s0, v254, 57
	v_readlane_b32 s1, v254, 58
	s_nop 1
	v_cndmask_b32_e64 v4, v12, 0, s[0:1]
	v_readlane_b32 s0, v254, 59
	v_readlane_b32 s1, v254, 60
	v_pk_add_f32 v[2:3], v[2:3], v[4:5]
	s_nop 0
	v_cndmask_b32_e64 v5, v31, 0, s[0:1]
	v_readlane_b32 s0, v254, 61
	v_readlane_b32 s1, v254, 62
	v_cvt_pk_bf16_f32 v2, v2, v3
	s_nop 0
	v_cndmask_b32_e64 v4, v30, 0, s[0:1]
	v_readlane_b32 s0, v254, 63
	v_readlane_b32 s1, v255, 0
	s_nop 1
	v_cndmask_b32_e64 v7, v15, 0, s[0:1]
	v_readlane_b32 s0, v255, 1
	v_readlane_b32 s1, v255, 2
	s_nop 1
	v_cndmask_b32_e64 v6, v14, 0, s[0:1]
	v_pk_add_f32 v[4:5], v[4:5], v[6:7]
	v_readlane_b32 s0, v255, 3
	v_cvt_pk_bf16_f32 v3, v4, v5
	ds_write2_b64 v151, v[0:1], v[2:3] offset0:4 offset1:6
	ds_read_b128 v[0:3], v187 offset:55296
	ds_read_b128 v[4:7], v150 offset:27648
	ds_read_b128 v[32:35], v187 offset:55328
	ds_read_b128 v[36:39], v150 offset:27680
	s_waitcnt lgkmcnt(2)
	v_mfma_f32_32x32x16_bf16 v[0:15], v[0:3], v[4:7], 0
	ds_read_b128 v[16:19], v187 offset:61440
	ds_read_b128 v[20:23], v152 offset:27648
	ds_read_b128 v[40:43], v187 offset:55360
	ds_read_b128 v[44:47], v150 offset:27712
	v_readlane_b32 s1, v255, 4
	s_waitcnt lgkmcnt(2)
	v_mfma_f32_32x32x16_bf16 v[16:31], v[16:19], v[20:23], 0
	v_mfma_f32_32x32x16_bf16 v[0:15], v[32:35], v[36:39], v[0:15]
	ds_read_b128 v[32:35], v187 offset:61472
	ds_read_b128 v[36:39], v152 offset:27680
	ds_read_b128 v[98:101], v187 offset:61504
	ds_read_b128 v[102:105], v152 offset:27712
	s_waitcnt lgkmcnt(2)
	v_mfma_f32_32x32x16_bf16 v[16:31], v[32:35], v[36:39], v[16:31]
	v_mfma_f32_32x32x16_bf16 v[0:15], v[40:43], v[44:47], v[0:15]
	s_waitcnt lgkmcnt(0)
	v_mfma_f32_32x32x16_bf16 v[16:31], v[98:101], v[102:105], v[16:31]
	s_nop 9
	v_cndmask_b32_e64 v1, v1, 0, s[0:1]
	v_readlane_b32 s0, v255, 5
	v_readlane_b32 s1, v255, 6
	s_nop 1
	v_cndmask_b32_e64 v0, v0, 0, s[0:1]
	v_readlane_b32 s0, v255, 7
	v_readlane_b32 s1, v255, 8
	s_nop 1
	v_cndmask_b32_e64 v17, v17, 0, s[0:1]
	v_readlane_b32 s0, v255, 9
	v_readlane_b32 s1, v255, 10
	s_nop 1
	v_cndmask_b32_e64 v16, v16, 0, s[0:1]
	v_readlane_b32 s0, v255, 11
	v_readlane_b32 s1, v255, 12
	v_pk_add_f32 v[0:1], v[0:1], v[16:17]
	s_nop 0
	v_cndmask_b32_e64 v3, v3, 0, s[0:1]
	v_readlane_b32 s0, v255, 13
	v_readlane_b32 s1, v255, 14
	v_cvt_pk_bf16_f32 v0, v0, v1
	s_nop 0
	v_cndmask_b32_e64 v2, v2, 0, s[0:1]
	v_readlane_b32 s0, v255, 15
	v_readlane_b32 s1, v255, 16
	s_nop 1
	v_cndmask_b32_e64 v17, v19, 0, s[0:1]
	v_readlane_b32 s0, v255, 17
	v_readlane_b32 s1, v255, 18
	s_nop 1
	v_cndmask_b32_e64 v16, v18, 0, s[0:1]
	v_readlane_b32 s0, v255, 19
	v_pk_add_f32 v[2:3], v[2:3], v[16:17]
	v_readlane_b32 s1, v255, 20
	v_cvt_pk_bf16_f32 v1, v2, v3
	s_nop 0
	v_cndmask_b32_e64 v3, v5, 0, s[0:1]
	v_readlane_b32 s0, v255, 21
	v_readlane_b32 s1, v255, 22
	s_nop 1
	v_cndmask_b32_e64 v2, v4, 0, s[0:1]
	v_readlane_b32 s0, v255, 23
	v_readlane_b32 s1, v255, 24
	s_nop 1
	v_cndmask_b32_e64 v5, v21, 0, s[0:1]
	v_readlane_b32 s0, v255, 25
	v_readlane_b32 s1, v255, 26
	s_nop 1
	v_cndmask_b32_e64 v4, v20, 0, s[0:1]
	v_readlane_b32 s0, v255, 27
	v_readlane_b32 s1, v255, 28
	v_pk_add_f32 v[2:3], v[2:3], v[4:5]
	s_nop 0
	v_cndmask_b32_e64 v5, v7, 0, s[0:1]
	v_readlane_b32 s0, v255, 29
	v_readlane_b32 s1, v255, 30
	v_cvt_pk_bf16_f32 v2, v2, v3
	s_nop 0
	v_cndmask_b32_e64 v4, v6, 0, s[0:1]
	v_readlane_b32 s0, v255, 31
	v_readlane_b32 s1, v255, 32
	v_cndmask_b32_e64 v6, v22, 0, s[24:25]
	s_nop 0
	v_cndmask_b32_e64 v7, v23, 0, s[0:1]
	v_pk_add_f32 v[4:5], v[4:5], v[6:7]
	v_cndmask_b32_e64 v7, v31, 0, s[56:57]
	v_cvt_pk_bf16_f32 v3, v4, v5
	ds_write2_b64 v151, v[0:1], v[2:3] offset0:8 offset1:10
	v_cndmask_b32_e64 v1, v9, 0, s[26:27]
	v_cndmask_b32_e64 v0, v8, 0, s[28:29]
	v_cndmask_b32_e64 v3, v25, 0, s[30:31]
	v_cndmask_b32_e64 v2, v24, 0, s[34:35]
	v_pk_add_f32 v[0:1], v[0:1], v[2:3]
	v_cndmask_b32_e64 v3, v11, 0, s[36:37]
	v_cndmask_b32_e64 v2, v10, 0, s[38:39]
	v_cndmask_b32_e64 v5, v27, 0, s[40:41]
	v_cndmask_b32_e64 v4, v26, 0, s[42:43]
	v_pk_add_f32 v[2:3], v[2:3], v[4:5]
	v_cvt_pk_bf16_f32 v0, v0, v1
	v_cvt_pk_bf16_f32 v1, v2, v3
	v_cndmask_b32_e64 v3, v13, 0, s[44:45]
	v_cndmask_b32_e64 v2, v12, 0, s[46:47]
	v_cndmask_b32_e64 v5, v29, 0, s[48:49]
	v_cndmask_b32_e64 v4, v28, 0, s[50:51]
	v_pk_add_f32 v[2:3], v[2:3], v[4:5]
	v_cndmask_b32_e64 v5, v15, 0, s[52:53]
	v_cndmask_b32_e64 v4, v14, 0, s[54:55]
	v_cndmask_b32_e64 v6, v30, 0, s[58:59]
	v_pk_add_f32 v[4:5], v[4:5], v[6:7]
	v_cvt_pk_bf16_f32 v2, v2, v3
	v_cvt_pk_bf16_f32 v3, v4, v5
	ds_write2_b64 v151, v[0:1], v[2:3] offset0:12 offset1:14
	s_waitcnt lgkmcnt(0)
	ds_read_b128 v[0:3], v189
	v_add_u32_e32 v12, v151, v186
	ds_read_b128 v[4:7], v12
	ds_read_b128 v[8:11], v189 offset:32
	ds_read_b128 v[130:133], v12 offset:32
	s_waitcnt lgkmcnt(2)
	v_mfma_f32_32x32x16_bf16 v[32:47], v[0:3], v[4:7], 0
	s_lshl_b32 s0, s17, 1
	s_add_i32 s0, s0, s6
	s_lshl_b32 s1, vcc_lo, 2
	s_mul_i32 s84, s0, 0x60
	s_add_i32 s16, s1, 0
	s_lshl_b32 s0, s84, 2
	s_add_i32 s16, s16, s0
	s_waitcnt lgkmcnt(0)
	v_mfma_f32_32x32x16_bf16 v[32:47], v[8:11], v[130:133], v[32:47]
	ds_read_b128 v[0:3], v189 offset:64
	ds_read_b128 v[126:129], v12 offset:64
	ds_read_b128 v[8:11], v189 offset:96
	ds_read_b128 v[118:121], v12 offset:96
	s_add_i32 s16, s16, 0x20400
	s_and_b64 s[0:1], s[60:61], exec
	v_readlane_b32 s0, v253, 42
	v_readlane_b32 s1, v253, 43
	s_movk_i32 s17, 0x140
	s_waitcnt lgkmcnt(2)
	v_mfma_f32_32x32x16_bf16 v[32:47], v[0:3], v[126:129], v[32:47]
	s_waitcnt lgkmcnt(0)
	v_mfma_f32_32x32x16_bf16 v[32:47], v[8:11], v[118:121], v[32:47]
	ds_read_b128 v[0:3], v190
	ds_read_b128 v[122:125], v191 offset:27648
	ds_read_b128 v[8:11], v190 offset:32
	ds_read_b128 v[12:15], v190 offset:64
	ds_read_b128 v[114:117], v191 offset:27680
	ds_read_b128 v[110:113], v191 offset:27712
	s_waitcnt lgkmcnt(4)
	v_mfma_f32_32x32x16_bf16 v[32:47], v[0:3], v[122:125], v[32:47]
	s_waitcnt lgkmcnt(1)
	v_mfma_f32_32x32x16_bf16 v[32:47], v[8:11], v[114:117], v[32:47]
	s_waitcnt lgkmcnt(0)
	v_mfma_f32_32x32x16_bf16 v[32:47], v[12:15], v[110:113], v[32:47]
	ds_read_b128 v[0:3], v192
	ds_read_b128 v[106:109], v193 offset:27648
	ds_read_b128 v[8:11], v192 offset:32
	ds_read_b128 v[12:15], v192 offset:64
	ds_read_b128 v[102:105], v193 offset:27680
	ds_read_b128 v[98:101], v193 offset:27712
	s_waitcnt lgkmcnt(4)
	v_mfma_f32_32x32x16_bf16 v[32:47], v[0:3], v[106:109], v[32:47]
	s_waitcnt lgkmcnt(1)
	v_mfma_f32_32x32x16_bf16 v[32:47], v[8:11], v[102:105], v[32:47]
	ds_read_b128 v[0:3], v189 offset:4608
	ds_read_b128 v[8:11], v189 offset:4640
	s_waitcnt lgkmcnt(1)
	v_mfma_f32_32x32x16_bf16 v[16:31], v[0:3], v[4:7], 0
	s_waitcnt lgkmcnt(0)
	v_mfma_f32_32x32x16_bf16 v[16:31], v[8:11], v[130:133], v[16:31]
	ds_read_b128 v[0:3], v189 offset:4672
	ds_read_b128 v[8:11], v189 offset:4704
	s_waitcnt lgkmcnt(1)
	v_mfma_f32_32x32x16_bf16 v[16:31], v[0:3], v[126:129], v[16:31]
	s_waitcnt lgkmcnt(0)
	v_mfma_f32_32x32x16_bf16 v[16:31], v[8:11], v[118:121], v[16:31]
	ds_read_b128 v[0:3], v198
	ds_read_b128 v[8:11], v198 offset:32
	s_waitcnt lgkmcnt(1)
	v_mfma_f32_32x32x16_bf16 v[16:31], v[0:3], v[122:125], v[16:31]
	s_waitcnt lgkmcnt(0)
	v_mfma_f32_32x32x16_bf16 v[16:31], v[8:11], v[114:117], v[16:31]
	ds_read_b128 v[0:3], v198 offset:64
	ds_read_b128 v[8:11], v199
	s_waitcnt lgkmcnt(1)
	v_mfma_f32_32x32x16_bf16 v[16:31], v[0:3], v[110:113], v[16:31]
	s_waitcnt lgkmcnt(0)
	v_mfma_f32_32x32x16_bf16 v[16:31], v[8:11], v[106:109], v[16:31]
	ds_read_b128 v[0:3], v199 offset:32
	ds_read_b128 v[8:11], v199 offset:64
	s_waitcnt lgkmcnt(1)
	v_mfma_f32_32x32x16_bf16 v[16:31], v[0:3], v[102:105], v[16:31]
	ds_read_b128 v[0:3], v189 offset:9216
	ds_read_b128 v[134:137], v189 offset:9248
	v_mfma_f32_32x32x16_bf16 v[32:47], v[12:15], v[98:101], v[32:47]
	s_waitcnt lgkmcnt(2)
	v_mfma_f32_32x32x16_bf16 v[16:31], v[8:11], v[98:101], v[16:31]
	s_nop 9
	v_add_f32_e32 v202, 0, v32
	v_add_f32_e32 v202, v33, v202
	v_add_f32_e32 v202, v34, v202
	v_add_f32_e32 v202, v35, v202
	s_waitcnt lgkmcnt(1)
	v_mfma_f32_32x32x16_bf16 v[0:15], v[0:3], v[4:7], 0
	s_waitcnt lgkmcnt(0)
	v_mfma_f32_32x32x16_bf16 v[0:15], v[134:137], v[130:133], v[0:15]
	ds_read_b128 v[130:133], v189 offset:9280
	ds_read_b128 v[134:137], v189 offset:9312
	s_waitcnt lgkmcnt(1)
	v_mfma_f32_32x32x16_bf16 v[0:15], v[130:133], v[126:129], v[0:15]
	s_waitcnt lgkmcnt(0)
	v_mfma_f32_32x32x16_bf16 v[0:15], v[134:137], v[118:121], v[0:15]
	ds_read_b128 v[118:121], v200
	ds_read_b128 v[126:129], v200 offset:32
	s_waitcnt lgkmcnt(1)
	v_mfma_f32_32x32x16_bf16 v[0:15], v[118:121], v[122:125], v[0:15]
	ds_read_b128 v[118:121], v200 offset:64
	ds_read_b128 v[122:125], v201
	ds_read_b128 v[130:133], v201 offset:32
	ds_read_b128 v[134:137], v201 offset:64
	s_waitcnt lgkmcnt(4)
	v_mfma_f32_32x32x16_bf16 v[0:15], v[126:129], v[114:117], v[0:15]
	v_add_f32_e32 v114, v36, v202
	v_add_f32_e32 v114, v37, v114
	v_add_f32_e32 v114, v38, v114
	v_add_f32_e32 v114, v39, v114
	v_add_f32_e32 v114, v40, v114
	v_add_f32_e32 v114, v41, v114
	v_add_f32_e32 v114, v42, v114
	s_waitcnt lgkmcnt(3)
	v_mfma_f32_32x32x16_bf16 v[0:15], v[118:121], v[110:113], v[0:15]
	v_add_f32_e32 v110, v43, v114
	v_add_f32_e32 v110, v44, v110
	v_add_f32_e32 v110, v45, v110
	v_add_f32_e32 v110, v46, v110
	v_add_f32_e32 v110, v47, v110
	v_add_f32_e32 v110, v110, v16
	v_add_f32_e32 v110, v17, v110
	s_waitcnt lgkmcnt(2)
	v_mfma_f32_32x32x16_bf16 v[0:15], v[122:125], v[106:109], v[0:15]
	v_add_f32_e32 v106, v18, v110
	v_add_f32_e32 v106, v19, v106
	v_add_f32_e32 v106, v20, v106
	v_add_f32_e32 v106, v21, v106
	v_add_f32_e32 v106, v22, v106
	v_add_f32_e32 v106, v23, v106
	v_add_f32_e32 v106, v24, v106
	s_waitcnt lgkmcnt(1)
	v_mfma_f32_32x32x16_bf16 v[0:15], v[130:133], v[102:105], v[0:15]
	v_add_f32_e32 v102, v25, v106
	v_add_f32_e32 v102, v26, v102
	v_add_f32_e32 v102, v27, v102
	v_add_f32_e32 v102, v28, v102
	v_add_f32_e32 v102, v29, v102
	v_add_f32_e32 v102, v30, v102
	v_add_f32_e32 v102, v31, v102
	s_waitcnt lgkmcnt(0)
	v_mfma_f32_32x32x16_bf16 v[0:15], v[134:137], v[98:101], v[0:15]
	v_lshlrev_b32_e32 v121, 2, v48
	s_nop 10
	v_add_f32_e32 v98, v102, v0
	v_add_f32_e32 v98, v1, v98
	v_add_f32_e32 v98, v2, v98
	v_add_f32_e32 v98, v3, v98
	v_add_f32_e32 v98, v4, v98
	v_add_f32_e32 v98, v5, v98
	v_add_f32_e32 v98, v6, v98
	v_add_f32_e32 v98, v7, v98
	v_add_f32_e32 v98, v8, v98
	v_add_f32_e32 v98, v9, v98
	v_add_f32_e32 v98, v10, v98
	v_add_f32_e32 v98, v11, v98
	v_add_f32_e32 v98, v12, v98
	v_add_f32_e32 v98, v13, v98
	v_add_f32_e32 v98, v14, v98
	v_add_f32_e32 v98, v15, v98
	ds_bpermute_b32 v48, v121, v98
	s_waitcnt lgkmcnt(0)
	v_add_f32_e32 v48, v98, v48
	v_lshlrev_b64 v[98:99], 11, v[182:183]
	v_lshl_add_u64 v[98:99], s[0:1], 0, v[98:99]
	s_movk_i32 s0, 0x780
	s_cselect_b32 s0, 0x300, s0
	s_ashr_i32 vcc_hi, vcc_lo, 31
	s_add_i32 s0, s84, s0
	v_lshl_add_u64 v[98:99], vcc, 1, v[98:99]
	s_ashr_i32 s85, s84, 31
	s_ashr_i32 s0, s0, 3
	v_mul_f32_e32 v48, 0x3c2aaaab, v48
	v_lshl_add_u64 v[114:115], s[84:85], 1, v[98:99]
	v_mov_b32_e32 v98, s0
	s_ashr_i32 s0, s0, 31
	v_cndmask_b32_e64 v120, 0, v48, s[60:61]
	v_mov_b32_e32 v99, s0
	v_alignbit_b32 v48, v183, v182, 6
	v_mad_u64_u32 v[98:99], s[0:1], v48, s17, v[98:99]
	v_mov_b32_e32 v48, v99
	v_lshrrev_b32_e32 v99, 6, v183
	v_mad_u64_u32 v[100:101], s[0:1], v99, s17, v[48:49]
	v_mov_b32_e32 v99, v100
	v_lshlrev_b64 v[98:99], 10, v[98:99]
	v_lshlrev_b32_e32 v48, 4, v182
	v_lshl_add_u64 v[98:99], s[70:71], 0, v[98:99]
	v_and_b32_e32 v48, 0x3f0, v48
	v_lshl_add_u64 v[98:99], v[98:99], 0, v[48:49]
	v_lshlrev_b32_e32 v48, 1, v156
	v_lshl_add_u64 v[102:103], v[98:99], 0, v[48:49]
	s_waitcnt vmcnt(0)
	v_lshrrev_b32_e32 v98, 6, v224
	v_mul_u32_u24_e32 v98, 0x1400, v98
	v_and_b32_e32 v100, 63, v224
	v_lshl_add_u32 v98, v100, 4, v98
	v_add_u32_e32 v98, 0x21000, v98
	ds_write_b128 v98, v[50:53]
	ds_write_b128 v98, v[54:57] offset:1024
	ds_write_b128 v98, v[58:61] offset:2048
	ds_write_b128 v98, v[62:65] offset:3072
	ds_write_b128 v98, v[66:69] offset:4096
	v_add_co_u32_e32 v104, vcc, 0x1000, v102
	s_nop 1
	v_addc_co_u32_e32 v105, vcc, 0, v103, vcc
	v_add_co_u32_e32 v106, vcc, 0x2000, v102
	s_nop 1
	v_addc_co_u32_e32 v107, vcc, 0, v103, vcc
	global_load_dwordx2 v[98:99], v[102:103], off
	global_load_dwordx2 v[100:101], v[102:103], off offset:1024
	global_load_dwordx2 v[50:51], v[102:103], off offset:2048
	global_load_dwordx2 v[52:53], v[102:103], off offset:3072
	global_load_dwordx2 v[54:55], v[104:105], off
	global_load_dwordx2 v[56:57], v[104:105], off offset:1024
	global_load_dwordx2 v[58:59], v[104:105], off offset:2048
	global_load_dwordx2 v[60:61], v[104:105], off offset:3072
	global_load_dwordx2 v[62:63], v[106:107], off
	global_load_dwordx2 v[64:65], v[106:107], off offset:1024
	global_load_dwordx2 v[66:67], v[106:107], off offset:2048
	global_load_dwordx2 v[68:69], v[106:107], off offset:3072
	v_pk_add_f32 v[204:205], v[32:33], v[120:121] op_sel_hi:[1,0] neg_lo:[0,1] neg_hi:[0,1]
	v_pk_add_f32 v[110:111], v[38:39], v[120:121] op_sel_hi:[1,0] neg_lo:[0,1] neg_hi:[0,1]
	v_pk_mul_f32 v[206:207], v[204:205], v[204:205]
	v_pk_add_f32 v[118:119], v[36:37], v[120:121] op_sel_hi:[1,0] neg_lo:[0,1] neg_hi:[0,1]
	v_pk_add_f32 v[108:109], v[40:41], v[120:121] op_sel_hi:[1,0] neg_lo:[0,1] neg_hi:[0,1]
	v_pk_add_f32 v[46:47], v[46:47], v[120:121] op_sel_hi:[1,0] neg_lo:[0,1] neg_hi:[0,1]
	v_pk_add_f32 v[38:39], v[22:23], v[120:121] op_sel_hi:[1,0] neg_lo:[0,1] neg_hi:[0,1]
	v_pk_add_f32 v[40:41], v[20:21], v[120:121] op_sel_hi:[1,0] neg_lo:[0,1] neg_hi:[0,1]
	v_pk_add_f32 v[32:33], v[26:27], v[120:121] op_sel_hi:[1,0] neg_lo:[0,1] neg_hi:[0,1]
	v_pk_add_f32 v[30:31], v[30:31], v[120:121] op_sel_hi:[1,0] neg_lo:[0,1] neg_hi:[0,1]
	v_pk_add_f32 v[28:29], v[28:29], v[120:121] op_sel_hi:[1,0] neg_lo:[0,1] neg_hi:[0,1]
	v_pk_add_f32 v[26:27], v[0:1], v[120:121] op_sel_hi:[1,0] neg_lo:[0,1] neg_hi:[0,1]
	v_pk_add_f32 v[20:21], v[6:7], v[120:121] op_sel_hi:[1,0] neg_lo:[0,1] neg_hi:[0,1]
	v_pk_add_f32 v[22:23], v[4:5], v[120:121] op_sel_hi:[1,0] neg_lo:[0,1] neg_hi:[0,1]
	v_pk_mul_f32 v[36:37], v[118:119], v[118:119]
	v_pk_mul_f32 v[208:209], v[110:111], v[110:111]
	v_pk_mul_f32 v[212:213], v[108:109], v[108:109]
	v_pk_mul_f32 v[214:215], v[46:47], v[46:47]
	v_pk_mul_f32 v[220:221], v[40:41], v[40:41]
	v_pk_mul_f32 v[218:219], v[38:39], v[38:39]
	v_pk_mul_f32 v[222:223], v[32:33], v[32:33]
	v_pk_mul_f32 v[246:247], v[28:29], v[28:29]
	v_pk_mul_f32 v[244:245], v[30:31], v[30:31]
	v_pk_mul_f32 v[0:1], v[26:27], v[26:27]
	v_pk_mul_f32 v[4:5], v[22:23], v[22:23]
	v_pk_mul_f32 v[6:7], v[20:21], v[20:21]
	s_waitcnt vmcnt(11)
	v_lshlrev_b32_e32 v234, 16, v98
	v_and_b32_e32 v235, 0xffff0000, v98
	v_mul_f32_e32 v98, 0xbfb8aa3b, v234
	v_exp_f32_e32 v104, v98
	v_mul_f32_e32 v98, 0xbfb8aa3b, v235
	v_exp_f32_e32 v105, v98
	v_lshlrev_b32_e32 v250, 16, v99
	v_and_b32_e32 v251, 0xffff0000, v99
	v_mul_f32_e32 v99, 0xbfb8aa3b, v251
	v_pk_add_f32 v[122:123], v[104:105], 1.0 op_sel_hi:[1,0]
	v_exp_f32_e32 v99, v99
	v_div_scale_f32 v98, s[0:1], v123, v123, v235
	v_rcp_f32_e32 v104, v98
	s_waitcnt vmcnt(10)
	v_lshlrev_b32_e32 v126, 16, v100
	v_and_b32_e32 v127, 0xffff0000, v100
	v_lshlrev_b32_e32 v130, 16, v101
	v_fma_f32 v105, -v98, v104, 1.0
	v_fmac_f32_e32 v104, v105, v104
	v_div_scale_f32 v105, vcc, v235, v123, v235
	v_mul_f32_e32 v106, v105, v104
	v_fma_f32 v107, -v98, v106, v105
	v_fmac_f32_e32 v106, v107, v104
	v_fma_f32 v98, -v98, v106, v105
	v_div_fmas_f32 v248, v98, v104, v106
	v_div_scale_f32 v98, s[0:1], v122, v122, v234
	v_rcp_f32_e32 v104, v98
	v_and_b32_e32 v131, 0xffff0000, v101
	v_fma_f32 v105, -v98, v104, 1.0
	v_fmac_f32_e32 v104, v105, v104
	v_div_scale_f32 v105, vcc, v234, v122, v234
	v_mul_f32_e32 v106, v105, v104
	v_fma_f32 v107, -v98, v106, v105
	v_fmac_f32_e32 v106, v107, v104
	v_fma_f32 v98, -v98, v106, v105
	v_div_fmas_f32 v249, v98, v104, v106
	v_mul_f32_e32 v98, 0xbfb8aa3b, v250
	v_exp_f32_e32 v98, v98
	s_nop 0
	v_pk_add_f32 v[124:125], v[98:99], 1.0 op_sel_hi:[1,0]
	s_nop 0
	v_div_scale_f32 v98, s[0:1], v125, v125, v251
	v_rcp_f32_e32 v99, v98
	s_nop 0
	v_fma_f32 v104, -v98, v99, 1.0
	v_fmac_f32_e32 v99, v104, v99
	v_div_scale_f32 v104, vcc, v251, v125, v251
	v_mul_f32_e32 v105, v104, v99
	v_fma_f32 v106, -v98, v105, v104
	v_fmac_f32_e32 v105, v106, v99
	v_fma_f32 v98, -v98, v105, v104
	v_div_fmas_f32 v233, v98, v99, v105
	v_div_scale_f32 v98, s[0:1], v124, v124, v250
	v_rcp_f32_e32 v99, v98
	s_nop 0
	v_fma_f32 v104, -v98, v99, 1.0
	v_fmac_f32_e32 v99, v104, v99
	v_div_scale_f32 v104, vcc, v250, v124, v250
	v_mul_f32_e32 v105, v104, v99
	v_fma_f32 v106, -v98, v105, v104
	v_fmac_f32_e32 v105, v106, v99
	v_fma_f32 v98, -v98, v105, v104
	v_div_fmas_f32 v238, v98, v99, v105
	v_mul_f32_e32 v98, 0xbfb8aa3b, v126
	v_mul_f32_e32 v99, 0xbfb8aa3b, v127
	v_exp_f32_e32 v98, v98
	v_exp_f32_e32 v99, v99
	v_pk_add_f32 v[106:107], v[42:43], v[120:121] op_sel_hi:[1,0] neg_lo:[0,1] neg_hi:[0,1]
	v_pk_add_f32 v[42:43], v[18:19], v[120:121] op_sel_hi:[1,0] neg_lo:[0,1] neg_hi:[0,1]
	v_pk_mul_f32 v[210:211], v[106:107], v[106:107]
	v_pk_add_f32 v[112:113], v[98:99], 1.0 op_sel_hi:[1,0]
	v_pk_mul_f32 v[18:19], v[42:43], v[42:43]
	v_div_scale_f32 v98, s[0:1], v113, v113, v127
	v_rcp_f32_e32 v99, v98
	s_nop 0
	v_fma_f32 v100, -v98, v99, 1.0
	v_fmac_f32_e32 v99, v100, v99
	v_div_scale_f32 v100, vcc, v127, v113, v127
	v_mul_f32_e32 v104, v100, v99
	v_fma_f32 v105, -v98, v104, v100
	v_fmac_f32_e32 v104, v105, v99
	v_fma_f32 v98, -v98, v104, v100
	v_div_fmas_f32 v128, v98, v99, v104
	v_div_scale_f32 v98, s[0:1], v112, v112, v126
	v_rcp_f32_e32 v99, v98
	v_div_fixup_f32 v127, v128, v113, v127
	v_fma_f32 v100, -v98, v99, 1.0
	v_fmac_f32_e32 v99, v100, v99
	v_div_scale_f32 v100, vcc, v126, v112, v126
	v_mul_f32_e32 v104, v100, v99
	v_fma_f32 v105, -v98, v104, v100
	v_fmac_f32_e32 v104, v105, v99
	v_fma_f32 v98, -v98, v104, v100
	v_div_fmas_f32 v129, v98, v99, v104
	v_mul_f32_e32 v98, 0xbfb8aa3b, v130
	v_mul_f32_e32 v99, 0xbfb8aa3b, v131
	v_exp_f32_e32 v98, v98
	v_exp_f32_e32 v99, v99
	v_div_fixup_f32 v126, v129, v112, v126
	v_pk_add_f32 v[116:117], v[98:99], 1.0 op_sel_hi:[1,0]
	s_nop 0
	v_div_scale_f32 v98, s[0:1], v117, v117, v131
	v_rcp_f32_e32 v99, v98
	s_nop 0
	v_fma_f32 v100, -v98, v99, 1.0
	v_fmac_f32_e32 v99, v100, v99
	v_div_scale_f32 v100, vcc, v131, v117, v131
	v_mul_f32_e32 v101, v100, v99
	v_fma_f32 v104, -v98, v101, v100
	v_fmac_f32_e32 v101, v104, v99
	v_fma_f32 v98, -v98, v101, v100
	v_div_fmas_f32 v132, v98, v99, v101
	v_div_scale_f32 v98, s[0:1], v116, v116, v130
	v_rcp_f32_e32 v99, v98
	s_mov_b64 s[0:1], 0x2db14200
	v_div_fixup_f32 v117, v132, v117, v131
	v_fma_f32 v100, -v98, v99, 1.0
	v_fmac_f32_e32 v99, v100, v99
	v_div_scale_f32 v100, vcc, v130, v116, v130
	v_mul_f32_e32 v101, v100, v99
	v_fma_f32 v104, -v98, v101, v100
	v_fmac_f32_e32 v101, v104, v99
	v_fma_f32 v98, -v98, v101, v100
	v_div_fmas_f32 v133, v98, v99, v101
	v_pk_add_f32 v[100:101], v[10:11], v[120:121] op_sel_hi:[1,0] neg_lo:[0,1] neg_hi:[0,1]
	v_pk_add_f32 v[10:11], v[34:35], v[120:121] op_sel_hi:[1,0] neg_lo:[0,1] neg_hi:[0,1]
	v_pk_add_f32 v[98:99], v[12:13], v[120:121] op_sel_hi:[1,0] neg_lo:[0,1] neg_hi:[0,1]
	v_pk_add_f32 v[12:13], v[14:15], v[120:121] op_sel_hi:[1,0] neg_lo:[0,1] neg_hi:[0,1]
	v_pk_mul_f32 v[202:203], v[10:11], v[10:11]
	v_pk_add_f32 v[104:105], v[44:45], v[120:121] op_sel_hi:[1,0] neg_lo:[0,1] neg_hi:[0,1]
	v_pk_add_f32 v[44:45], v[16:17], v[120:121] op_sel_hi:[1,0] neg_lo:[0,1] neg_hi:[0,1]
	v_pk_add_f32 v[34:35], v[24:25], v[120:121] op_sel_hi:[1,0] neg_lo:[0,1] neg_hi:[0,1]
	v_pk_add_f32 v[24:25], v[2:3], v[120:121] op_sel_hi:[1,0] neg_lo:[0,1] neg_hi:[0,1]
	v_pk_add_f32 v[14:15], v[8:9], v[120:121] op_sel_hi:[1,0] neg_lo:[0,1] neg_hi:[0,1]
	v_add_f32_e32 v120, v206, v207
	v_add_f32_e32 v120, v202, v120
	v_add_f32_e32 v120, v203, v120
	v_add_f32_e32 v36, v36, v120
	v_add_f32_e32 v36, v37, v36
	v_add_f32_e32 v36, v208, v36
	v_add_f32_e32 v36, v209, v36
	v_add_f32_e32 v36, v212, v36
	v_add_f32_e32 v36, v213, v36
	v_add_f32_e32 v36, v210, v36
	v_pk_mul_f32 v[216:217], v[104:105], v[104:105]
	v_add_f32_e32 v36, v211, v36
	v_add_f32_e32 v36, v216, v36
	v_add_f32_e32 v36, v217, v36
	v_add_f32_e32 v36, v214, v36
	v_pk_mul_f32 v[16:17], v[44:45], v[44:45]
	v_add_f32_e32 v36, v215, v36
	v_add_f32_e32 v16, v16, v36
	v_add_f32_e32 v16, v17, v16
	v_add_f32_e32 v16, v18, v16
	v_add_f32_e32 v16, v19, v16
	v_add_f32_e32 v16, v220, v16
	v_add_f32_e32 v16, v221, v16
	v_add_f32_e32 v16, v218, v16
	v_pk_mul_f32 v[242:243], v[34:35], v[34:35]
	v_add_f32_e32 v16, v219, v16
	v_add_f32_e32 v16, v242, v16
	v_add_f32_e32 v16, v243, v16
	v_add_f32_e32 v16, v222, v16
	v_add_f32_e32 v16, v223, v16
	v_add_f32_e32 v16, v246, v16
	v_add_f32_e32 v16, v247, v16
	v_add_f32_e32 v16, v244, v16
	v_add_f32_e32 v16, v245, v16
	v_add_f32_e32 v0, v0, v16
	v_pk_mul_f32 v[2:3], v[24:25], v[24:25]
	v_add_f32_e32 v0, v1, v0
	v_add_f32_e32 v0, v2, v0
	v_add_f32_e32 v0, v3, v0
	v_add_f32_e32 v0, v4, v0
	v_add_f32_e32 v0, v5, v0
	v_add_f32_e32 v0, v6, v0
	v_pk_mul_f32 v[8:9], v[14:15], v[14:15]
	v_add_f32_e32 v0, v7, v0
	v_add_f32_e32 v0, v8, v0
	v_pk_mul_f32 v[134:135], v[100:101], v[100:101]
	v_add_f32_e32 v0, v9, v0
	v_add_f32_e32 v0, v134, v0
	v_pk_mul_f32 v[136:137], v[98:99], v[98:99]
	v_add_f32_e32 v0, v135, v0
	v_add_f32_e32 v0, v136, v0
	v_pk_mul_f32 v[182:183], v[12:13], v[12:13]
	v_add_f32_e32 v0, v137, v0
	v_add_f32_e32 v0, v182, v0
	v_add_f32_e32 v0, v183, v0
	ds_bpermute_b32 v1, v121, v0
	v_lshl_add_u32 v19, v156, 2, s16
	ds_read_b128 v[4:7], v19
	v_lshl_add_u64 v[36:37], v[114:115], 0, s[0:1]
	v_div_fixup_f32 v115, v248, v123, v235
	s_waitcnt lgkmcnt(1)
	v_add_f32_e32 v0, v0, v1
	v_fmamk_f32 v0, v0, 0x3c2aaaab, v232
	v_mul_f32_e32 v1, 0x4b800000, v0
	v_cmp_gt_f32_e32 vcc, s92, v0
	v_div_fixup_f32 v114, v249, v122, v234
	v_div_fixup_f32 v9, v233, v125, v251
	v_cndmask_b32_e32 v0, v0, v1, vcc
	v_rsq_f32_e32 v0, v0
	v_div_fixup_f32 v8, v238, v124, v250
	v_lshl_add_u64 v[16:17], v[36:37], 0, v[48:49]
	v_div_fixup_f32 v116, v133, v116, v130
	v_mul_f32_e32 v1, 0x45800000, v0
	v_cndmask_b32_e32 v18, v0, v1, vcc
	v_pk_mul_f32 v[120:121], v[204:205], v[18:19] op_sel_hi:[1,0]
	v_pk_mul_f32 v[10:11], v[10:11], v[18:19] op_sel_hi:[1,0]
	s_waitcnt lgkmcnt(0)
	v_pk_mul_f32 v[4:5], v[4:5], v[120:121]
	v_pk_mul_f32 v[6:7], v[6:7], v[10:11]
	v_pk_mul_f32 v[4:5], v[114:115], v[4:5]
	v_pk_mul_f32 v[6:7], v[8:9], v[6:7]
	v_cvt_pk_bf16_f32 v4, v4, v5
	v_cvt_pk_bf16_f32 v5, v6, v7
	global_store_dwordx2 v[16:17], v[4:5], off
	ds_read_b128 v[0:3], v19 offset:256
	v_pk_mul_f32 v[118:119], v[118:119], v[18:19] op_sel_hi:[1,0]
	v_pk_mul_f32 v[110:111], v[110:111], v[18:19] op_sel_hi:[1,0]
	v_lshlrev_b32_e32 v48, 1, v158
	v_lshl_add_u64 v[112:113], v[36:37], 0, v[48:49]
	v_pk_mul_f32 v[108:109], v[108:109], v[18:19] op_sel_hi:[1,0]
	v_pk_mul_f32 v[106:107], v[106:107], v[18:19] op_sel_hi:[1,0]
	v_pk_mul_f32 v[46:47], v[46:47], v[18:19] op_sel_hi:[1,0]
	v_pk_mul_f32 v[44:45], v[44:45], v[18:19] op_sel_hi:[1,0]
	v_pk_mul_f32 v[42:43], v[42:43], v[18:19] op_sel_hi:[1,0]
	v_pk_mul_f32 v[38:39], v[38:39], v[18:19] op_sel_hi:[1,0]
	v_pk_mul_f32 v[34:35], v[34:35], v[18:19] op_sel_hi:[1,0]
	v_pk_mul_f32 v[32:33], v[32:33], v[18:19] op_sel_hi:[1,0]
	v_pk_mul_f32 v[28:29], v[28:29], v[18:19] op_sel_hi:[1,0]
	v_pk_mul_f32 v[30:31], v[30:31], v[18:19] op_sel_hi:[1,0]
	v_pk_mul_f32 v[26:27], v[26:27], v[18:19] op_sel_hi:[1,0]
	v_pk_mul_f32 v[22:23], v[22:23], v[18:19] op_sel_hi:[1,0]
	v_pk_mul_f32 v[20:21], v[20:21], v[18:19] op_sel_hi:[1,0]
	s_waitcnt vmcnt(10)
	v_mov_b32_e32 v4, v50
	v_mov_b32_e32 v5, v51
	v_lshlrev_b32_e32 v134, 16, v4
	v_and_b32_e32 v135, 0xffff0000, v4
	v_mul_f32_e32 v4, 0xbfb8aa3b, v134
	v_exp_f32_e32 v6, v4
	v_mul_f32_e32 v4, 0xbfb8aa3b, v135
	v_exp_f32_e32 v7, v4
	v_lshlrev_b32_e32 v182, 16, v5
	v_and_b32_e32 v183, 0xffff0000, v5
	v_mul_f32_e32 v5, 0xbfb8aa3b, v183
	v_pk_add_f32 v[122:123], v[6:7], 1.0 op_sel_hi:[1,0]
	v_exp_f32_e32 v5, v5
	v_div_scale_f32 v4, s[0:1], v123, v123, v135
	v_rcp_f32_e32 v6, v4
	s_nop 0
	v_fma_f32 v7, -v4, v6, 1.0
	v_fmac_f32_e32 v6, v7, v6
	v_div_scale_f32 v7, vcc, v135, v123, v135
	v_mul_f32_e32 v8, v7, v6
	v_fma_f32 v9, -v4, v8, v7
	v_fmac_f32_e32 v8, v9, v6
	v_fma_f32 v4, -v4, v8, v7
	v_div_fmas_f32 v136, v4, v6, v8
	v_div_scale_f32 v4, s[0:1], v122, v122, v134
	v_rcp_f32_e32 v6, v4
	s_nop 0
	v_fma_f32 v7, -v4, v6, 1.0
	v_fmac_f32_e32 v6, v7, v6
	v_div_scale_f32 v7, vcc, v134, v122, v134
	v_mul_f32_e32 v8, v7, v6
	v_fma_f32 v9, -v4, v8, v7
	v_fmac_f32_e32 v8, v9, v6
	v_fma_f32 v4, -v4, v8, v7
	v_div_fmas_f32 v137, v4, v6, v8
	v_mul_f32_e32 v4, 0xbfb8aa3b, v182
	v_exp_f32_e32 v4, v4
	s_nop 0
	v_pk_add_f32 v[124:125], v[4:5], 1.0 op_sel_hi:[1,0]
	s_nop 0
	v_div_scale_f32 v4, s[0:1], v125, v125, v183
	v_rcp_f32_e32 v5, v4
	s_nop 0
	v_fma_f32 v6, -v4, v5, 1.0
	v_fmac_f32_e32 v5, v6, v5
	v_div_scale_f32 v6, vcc, v183, v125, v183
	v_mul_f32_e32 v7, v6, v5
	v_fma_f32 v8, -v4, v7, v6
	v_fmac_f32_e32 v7, v8, v5
	v_fma_f32 v4, -v4, v7, v6
	v_div_fmas_f32 v202, v4, v5, v7
	v_div_scale_f32 v4, s[0:1], v124, v124, v182
	v_rcp_f32_e32 v5, v4
	s_movk_i32 s0, 0x1000
	v_fma_f32 v6, -v4, v5, 1.0
	v_fmac_f32_e32 v5, v6, v5
	v_div_scale_f32 v6, vcc, v182, v124, v182
	v_mul_f32_e32 v7, v6, v5
	v_fma_f32 v8, -v4, v7, v6
	v_fmac_f32_e32 v7, v8, v5
	v_fma_f32 v4, -v4, v7, v6
	v_div_fmas_f32 v203, v4, v5, v7
	v_lshl_add_u32 v4, v158, 2, s16
	ds_read_b128 v[8:11], v4
	v_add_co_u32_e32 v120, vcc, s0, v102
	s_movk_i32 s0, 0x2000
	s_nop 0
	v_addc_co_u32_e32 v121, vcc, 0, v103, vcc
	s_waitcnt lgkmcnt(0)
	v_pk_mul_f32 v[8:9], v[8:9], v[118:119]
	v_pk_mul_f32 v[10:11], v[10:11], v[110:111]
	v_pk_mul_f32 v[8:9], v[126:127], v[8:9]
	v_pk_mul_f32 v[10:11], v[116:117], v[10:11]
	v_cvt_pk_bf16_f32 v8, v8, v9
	v_cvt_pk_bf16_f32 v9, v10, v11
	global_store_dwordx2 v[112:113], v[8:9], off
	v_add_co_u32_e32 v114, vcc, s0, v102
	ds_read_b128 v[4:7], v19 offset:352
	s_nop 0
	v_addc_co_u32_e32 v115, vcc, 0, v103, vcc
	v_pk_mul_f32 v[0:1], v[0:1], v[26:27]
	s_waitcnt vmcnt(10)
	v_mov_b32_e32 v8, v52
	v_mov_b32_e32 v9, v53
	v_lshlrev_b32_e32 v126, 16, v8
	v_and_b32_e32 v127, 0xffff0000, v8
	v_mul_f32_e32 v8, 0xbfb8aa3b, v126
	v_exp_f32_e32 v10, v8
	v_mul_f32_e32 v8, 0xbfb8aa3b, v127
	v_exp_f32_e32 v11, v8
	v_lshlrev_b32_e32 v130, 16, v9
	v_and_b32_e32 v131, 0xffff0000, v9
	v_mul_f32_e32 v9, 0xbfb8aa3b, v131
	v_pk_add_f32 v[102:103], v[10:11], 1.0 op_sel_hi:[1,0]
	v_exp_f32_e32 v9, v9
	v_div_scale_f32 v8, s[0:1], v103, v103, v127
	v_rcp_f32_e32 v10, v8
	s_nop 0
	v_fma_f32 v11, -v8, v10, 1.0
	v_fmac_f32_e32 v10, v11, v10
	v_div_scale_f32 v11, vcc, v127, v103, v127
	v_mul_f32_e32 v48, v11, v10
	v_fma_f32 v110, -v8, v48, v11
	v_fmac_f32_e32 v48, v110, v10
	v_fma_f32 v8, -v8, v48, v11
	v_div_fmas_f32 v128, v8, v10, v48
	v_div_scale_f32 v8, s[0:1], v102, v102, v126
	v_rcp_f32_e32 v10, v8
	v_div_fixup_f32 v103, v128, v103, v127
	v_fma_f32 v11, -v8, v10, 1.0
	v_fmac_f32_e32 v10, v11, v10
	v_div_scale_f32 v11, vcc, v126, v102, v126
	v_mul_f32_e32 v48, v11, v10
	v_fma_f32 v110, -v8, v48, v11
	v_fmac_f32_e32 v48, v110, v10
	v_fma_f32 v8, -v8, v48, v11
	v_div_fmas_f32 v129, v8, v10, v48
	v_mul_f32_e32 v8, 0xbfb8aa3b, v130
	v_exp_f32_e32 v8, v8
	v_div_fixup_f32 v102, v129, v102, v126
	v_pk_add_f32 v[116:117], v[8:9], 1.0 op_sel_hi:[1,0]
	s_nop 0
	v_div_scale_f32 v8, s[0:1], v117, v117, v131
	v_rcp_f32_e32 v9, v8
	s_nop 0
	v_fma_f32 v10, -v8, v9, 1.0
	v_fmac_f32_e32 v9, v10, v9
	v_div_scale_f32 v10, vcc, v131, v117, v131
	v_mul_f32_e32 v11, v10, v9
	v_fma_f32 v48, -v8, v11, v10
	v_fmac_f32_e32 v11, v48, v9
	v_fma_f32 v8, -v8, v11, v10
	v_div_fmas_f32 v132, v8, v9, v11
	v_div_scale_f32 v8, s[0:1], v116, v116, v130
	v_rcp_f32_e32 v9, v8
	s_nop 0
	v_fma_f32 v10, -v8, v9, 1.0
	v_fmac_f32_e32 v9, v10, v9
	v_div_scale_f32 v10, vcc, v130, v116, v130
	v_mul_f32_e32 v11, v10, v9
	v_fma_f32 v48, -v8, v11, v10
	v_fmac_f32_e32 v11, v48, v9
	v_fma_f32 v8, -v8, v11, v10
	v_div_fmas_f32 v133, v8, v9, v11
	v_lshl_add_u32 v8, v160, 2, s16
	ds_read_b128 v[8:11], v8
	v_lshlrev_b32_e32 v48, 1, v160
	v_lshl_add_u64 v[118:119], v[36:37], 0, v[48:49]
	v_lshl_add_u32 v48, v162, 2, s16
	ds_read_b128 v[110:113], v48
	s_waitcnt lgkmcnt(1)
	v_pk_mul_f32 v[8:9], v[8:9], v[108:109]
	v_div_fixup_f32 v109, v136, v123, v135
	v_div_fixup_f32 v108, v137, v122, v134
	v_pk_mul_f32 v[10:11], v[10:11], v[106:107]
	v_div_fixup_f32 v107, v202, v125, v183
	v_div_fixup_f32 v106, v203, v124, v182
	v_pk_mul_f32 v[8:9], v[108:109], v[8:9]
	v_pk_mul_f32 v[10:11], v[106:107], v[10:11]
	v_cvt_pk_bf16_f32 v8, v8, v9
	v_cvt_pk_bf16_f32 v9, v10, v11
	global_store_dwordx2 v[118:119], v[8:9], off
	s_waitcnt lgkmcnt(0)
	v_pk_mul_f32 v[46:47], v[112:113], v[46:47]
	s_waitcnt vmcnt(10)
	v_mov_b32_e32 v8, v54
	v_mov_b32_e32 v9, v55
	v_lshlrev_b32_e32 v118, 16, v8
	v_and_b32_e32 v119, 0xffff0000, v8
	v_mul_f32_e32 v8, 0xbfb8aa3b, v118
	v_exp_f32_e32 v10, v8
	v_mul_f32_e32 v8, 0xbfb8aa3b, v119
	v_exp_f32_e32 v11, v8
	v_lshlrev_b32_e32 v124, 16, v9
	v_and_b32_e32 v125, 0xffff0000, v9
	v_mul_f32_e32 v9, 0xbfb8aa3b, v125
	v_pk_add_f32 v[106:107], v[10:11], 1.0 op_sel_hi:[1,0]
	v_exp_f32_e32 v9, v9
	v_div_scale_f32 v8, s[0:1], v107, v107, v119
	v_rcp_f32_e32 v10, v8
	s_nop 0
	v_fma_f32 v11, -v8, v10, 1.0
	v_fmac_f32_e32 v10, v11, v10
	v_div_scale_f32 v11, vcc, v119, v107, v119
	v_mul_f32_e32 v48, v11, v10
	v_fma_f32 v108, -v8, v48, v11
	v_fmac_f32_e32 v48, v108, v10
	v_fma_f32 v8, -v8, v48, v11
	v_div_fmas_f32 v122, v8, v10, v48
	v_div_scale_f32 v8, s[0:1], v106, v106, v118
	v_rcp_f32_e32 v10, v8
	s_nop 0
	v_fma_f32 v11, -v8, v10, 1.0
	v_fmac_f32_e32 v10, v11, v10
	v_div_scale_f32 v11, vcc, v118, v106, v118
	v_mul_f32_e32 v48, v11, v10
	v_fma_f32 v108, -v8, v48, v11
	v_fmac_f32_e32 v48, v108, v10
	v_fma_f32 v8, -v8, v48, v11
	v_div_fmas_f32 v123, v8, v10, v48
	v_mul_f32_e32 v8, 0xbfb8aa3b, v124
	v_exp_f32_e32 v8, v8
	s_nop 0
	v_pk_add_f32 v[108:109], v[8:9], 1.0 op_sel_hi:[1,0]
	s_nop 0
	v_div_scale_f32 v8, s[0:1], v109, v109, v125
	v_rcp_f32_e32 v9, v8
	s_nop 0
	v_fma_f32 v10, -v8, v9, 1.0
	v_fmac_f32_e32 v9, v10, v9
	v_div_scale_f32 v10, vcc, v125, v109, v125
	v_mul_f32_e32 v11, v10, v9
	v_fma_f32 v48, -v8, v11, v10
	v_fmac_f32_e32 v11, v48, v9
	v_fma_f32 v8, -v8, v11, v10
	v_div_fmas_f32 v134, v8, v9, v11
	v_div_scale_f32 v8, s[0:1], v108, v108, v124
	v_rcp_f32_e32 v9, v8
	s_nop 0
	v_fma_f32 v10, -v8, v9, 1.0
	v_fmac_f32_e32 v9, v10, v9
	v_div_scale_f32 v10, vcc, v124, v108, v124
	v_mul_f32_e32 v11, v10, v9
	v_fma_f32 v48, -v8, v11, v10
	v_fmac_f32_e32 v11, v48, v9
	v_fma_f32 v8, -v8, v11, v10
	v_div_fmas_f32 v135, v8, v9, v11
	v_pk_mul_f32 v[10:11], v[104:105], v[18:19] op_sel_hi:[1,0]
	v_lshlrev_b32_e32 v48, 1, v162
	v_pk_mul_f32 v[10:11], v[110:111], v[10:11]
	v_lshl_add_u64 v[8:9], v[36:37], 0, v[48:49]
	v_pk_mul_f32 v[10:11], v[102:103], v[10:11]
	v_div_fixup_f32 v103, v132, v117, v131
	v_div_fixup_f32 v102, v133, v116, v130
	v_pk_mul_f32 v[46:47], v[102:103], v[46:47]
	v_cvt_pk_bf16_f32 v10, v10, v11
	v_cvt_pk_bf16_f32 v11, v46, v47
	global_store_dwordx2 v[8:9], v[10:11], off
	s_waitcnt vmcnt(10)
	v_mov_b32_e32 v8, v56
	v_mov_b32_e32 v9, v57
	v_lshlrev_b32_e32 v116, 16, v8
	v_and_b32_e32 v117, 0xffff0000, v8
	v_mul_f32_e32 v8, 0xbfb8aa3b, v116
	v_exp_f32_e32 v10, v8
	v_mul_f32_e32 v8, 0xbfb8aa3b, v117
	v_exp_f32_e32 v11, v8
	v_lshlrev_b32_e32 v128, 16, v9
	v_and_b32_e32 v129, 0xffff0000, v9
	v_mul_f32_e32 v9, 0xbfb8aa3b, v129
	v_pk_add_f32 v[46:47], v[10:11], 1.0 op_sel_hi:[1,0]
	v_exp_f32_e32 v9, v9
	v_div_scale_f32 v8, s[0:1], v47, v47, v117
	v_rcp_f32_e32 v10, v8
	s_nop 0
	v_fma_f32 v11, -v8, v10, 1.0
	v_fmac_f32_e32 v10, v11, v10
	v_div_scale_f32 v11, vcc, v117, v47, v117
	v_mul_f32_e32 v48, v11, v10
	v_fma_f32 v102, -v8, v48, v11
	v_fmac_f32_e32 v48, v102, v10
	v_fma_f32 v8, -v8, v48, v11
	v_div_fmas_f32 v126, v8, v10, v48
	v_div_scale_f32 v8, s[0:1], v46, v46, v116
	v_rcp_f32_e32 v10, v8
	s_nop 0
	v_fma_f32 v11, -v8, v10, 1.0
	v_fmac_f32_e32 v10, v11, v10
	v_div_scale_f32 v11, vcc, v116, v46, v116
	v_mul_f32_e32 v48, v11, v10
	v_fma_f32 v102, -v8, v48, v11
	v_fmac_f32_e32 v48, v102, v10
	v_fma_f32 v8, -v8, v48, v11
	v_div_fmas_f32 v127, v8, v10, v48
	v_mul_f32_e32 v8, 0xbfb8aa3b, v128
	v_exp_f32_e32 v8, v8
	s_nop 0
	v_pk_add_f32 v[110:111], v[8:9], 1.0 op_sel_hi:[1,0]
	s_nop 0
	v_div_scale_f32 v8, s[0:1], v111, v111, v129
	v_rcp_f32_e32 v9, v8
	s_nop 0
	v_fma_f32 v10, -v8, v9, 1.0
	v_fmac_f32_e32 v9, v10, v9
	v_div_scale_f32 v10, vcc, v129, v111, v129
	v_mul_f32_e32 v11, v10, v9
	v_fma_f32 v48, -v8, v11, v10
	v_fmac_f32_e32 v11, v48, v9
	v_fma_f32 v8, -v8, v11, v10
	v_div_fmas_f32 v130, v8, v9, v11
	v_div_scale_f32 v8, s[0:1], v110, v110, v128
	v_rcp_f32_e32 v9, v8
	s_nop 0
	v_fma_f32 v10, -v8, v9, 1.0
	v_fmac_f32_e32 v9, v10, v9
	v_div_scale_f32 v10, vcc, v128, v110, v128
	v_mul_f32_e32 v11, v10, v9
	v_fma_f32 v48, -v8, v11, v10
	v_fmac_f32_e32 v11, v48, v9
	v_fma_f32 v8, -v8, v11, v10
	v_div_fmas_f32 v131, v8, v9, v11
	v_lshl_add_u32 v8, v174, 2, s16
	ds_read_b128 v[8:11], v8
	v_lshlrev_b32_e32 v48, 1, v174
	v_lshl_add_u64 v[112:113], v[36:37], 0, v[48:49]
	v_lshl_add_u32 v48, v176, 2, s16
	ds_read_b128 v[102:105], v48
	s_waitcnt lgkmcnt(1)
	v_pk_mul_f32 v[8:9], v[8:9], v[44:45]
	v_div_fixup_f32 v45, v122, v107, v119
	v_div_fixup_f32 v44, v123, v106, v118
	v_pk_mul_f32 v[10:11], v[10:11], v[42:43]
	v_div_fixup_f32 v43, v134, v109, v125
	v_div_fixup_f32 v42, v135, v108, v124
	v_pk_mul_f32 v[8:9], v[44:45], v[8:9]
	v_pk_mul_f32 v[10:11], v[42:43], v[10:11]
	v_cvt_pk_bf16_f32 v8, v8, v9
	v_cvt_pk_bf16_f32 v9, v10, v11
	global_store_dwordx2 v[112:113], v[8:9], off
	s_waitcnt lgkmcnt(0)
	v_pk_mul_f32 v[38:39], v[104:105], v[38:39]
	s_waitcnt vmcnt(10)
	v_mov_b32_e32 v8, v58
	v_mov_b32_e32 v9, v59
	v_lshlrev_b32_e32 v106, 16, v8
	v_and_b32_e32 v107, 0xffff0000, v8
	v_mul_f32_e32 v8, 0xbfb8aa3b, v106
	v_exp_f32_e32 v10, v8
	v_mul_f32_e32 v8, 0xbfb8aa3b, v107
	v_exp_f32_e32 v11, v8
	v_lshlrev_b32_e32 v112, 16, v9
	v_and_b32_e32 v113, 0xffff0000, v9
	v_mul_f32_e32 v9, 0xbfb8aa3b, v113
	v_pk_add_f32 v[42:43], v[10:11], 1.0 op_sel_hi:[1,0]
	v_exp_f32_e32 v9, v9
	v_div_scale_f32 v8, s[0:1], v43, v43, v107
	v_rcp_f32_e32 v10, v8
	s_nop 0
	v_fma_f32 v11, -v8, v10, 1.0
	v_fmac_f32_e32 v10, v11, v10
	v_div_scale_f32 v11, vcc, v107, v43, v107
	v_mul_f32_e32 v44, v11, v10
	v_fma_f32 v45, -v8, v44, v11
	v_fmac_f32_e32 v44, v45, v10
	v_fma_f32 v8, -v8, v44, v11
	v_div_fmas_f32 v108, v8, v10, v44
	v_div_scale_f32 v8, s[0:1], v42, v42, v106
	v_rcp_f32_e32 v10, v8
	s_nop 0
	v_fma_f32 v11, -v8, v10, 1.0
	v_fmac_f32_e32 v10, v11, v10
	v_div_scale_f32 v11, vcc, v106, v42, v106
	v_mul_f32_e32 v44, v11, v10
	v_fma_f32 v45, -v8, v44, v11
	v_fmac_f32_e32 v44, v45, v10
	v_fma_f32 v8, -v8, v44, v11
	v_div_fmas_f32 v109, v8, v10, v44
	v_mul_f32_e32 v8, 0xbfb8aa3b, v112
	v_exp_f32_e32 v8, v8
	s_nop 0
	v_pk_add_f32 v[44:45], v[8:9], 1.0 op_sel_hi:[1,0]
	s_nop 0
	v_div_scale_f32 v8, s[0:1], v45, v45, v113
	v_rcp_f32_e32 v9, v8
	s_nop 0
	v_fma_f32 v10, -v8, v9, 1.0
	v_fmac_f32_e32 v9, v10, v9
	v_div_scale_f32 v10, vcc, v113, v45, v113
	v_mul_f32_e32 v11, v10, v9
	v_fma_f32 v48, -v8, v11, v10
	v_fmac_f32_e32 v11, v48, v9
	v_fma_f32 v8, -v8, v11, v10
	v_div_fmas_f32 v118, v8, v9, v11
	v_div_scale_f32 v8, s[0:1], v44, v44, v112
	v_rcp_f32_e32 v9, v8
	s_nop 0
	v_fma_f32 v10, -v8, v9, 1.0
	v_fmac_f32_e32 v9, v10, v9
	v_div_scale_f32 v10, vcc, v112, v44, v112
	v_mul_f32_e32 v11, v10, v9
	v_fma_f32 v48, -v8, v11, v10
	v_fmac_f32_e32 v11, v48, v9
	v_fma_f32 v8, -v8, v11, v10
	v_div_fmas_f32 v119, v8, v9, v11
	v_pk_mul_f32 v[10:11], v[40:41], v[18:19] op_sel_hi:[1,0]
	v_div_fixup_f32 v41, v126, v47, v117
	v_pk_mul_f32 v[10:11], v[102:103], v[10:11]
	v_div_fixup_f32 v40, v127, v46, v116
	v_pk_mul_f32 v[10:11], v[40:41], v[10:11]
	v_div_fixup_f32 v41, v130, v111, v129
	v_div_fixup_f32 v40, v131, v110, v128
	v_lshlrev_b32_e32 v48, 1, v176
	v_pk_mul_f32 v[38:39], v[40:41], v[38:39]
	v_lshl_add_u64 v[8:9], v[36:37], 0, v[48:49]
	v_cvt_pk_bf16_f32 v10, v10, v11
	v_cvt_pk_bf16_f32 v11, v38, v39
	global_store_dwordx2 v[8:9], v[10:11], off
	v_lshlrev_b32_e32 v48, 1, v178
	v_lshl_add_u64 v[104:105], v[36:37], 0, v[48:49]
	s_waitcnt vmcnt(10)
	v_mov_b32_e32 v8, v60
	v_mov_b32_e32 v9, v61
	v_lshlrev_b32_e32 v110, 16, v8
	v_and_b32_e32 v111, 0xffff0000, v8
	v_mul_f32_e32 v8, 0xbfb8aa3b, v110
	v_exp_f32_e32 v10, v8
	v_mul_f32_e32 v8, 0xbfb8aa3b, v111
	v_exp_f32_e32 v11, v8
	v_lshlrev_b32_e32 v120, 16, v9
	v_and_b32_e32 v121, 0xffff0000, v9
	v_mul_f32_e32 v9, 0xbfb8aa3b, v121
	v_pk_add_f32 v[46:47], v[10:11], 1.0 op_sel_hi:[1,0]
	v_exp_f32_e32 v9, v9
	v_div_scale_f32 v8, s[0:1], v47, v47, v111
	v_rcp_f32_e32 v10, v8
	s_nop 0
	v_fma_f32 v11, -v8, v10, 1.0
	v_fmac_f32_e32 v10, v11, v10
	v_div_scale_f32 v11, vcc, v111, v47, v111
	v_mul_f32_e32 v38, v11, v10
	v_fma_f32 v39, -v8, v38, v11
	v_fmac_f32_e32 v38, v39, v10
	v_fma_f32 v8, -v8, v38, v11
	v_div_fmas_f32 v116, v8, v10, v38
	v_div_scale_f32 v8, s[0:1], v46, v46, v110
	v_rcp_f32_e32 v10, v8
	s_nop 0
	v_fma_f32 v11, -v8, v10, 1.0
	v_fmac_f32_e32 v10, v11, v10
	v_div_scale_f32 v11, vcc, v110, v46, v110
	v_mul_f32_e32 v38, v11, v10
	v_fma_f32 v39, -v8, v38, v11
	v_fmac_f32_e32 v38, v39, v10
	v_fma_f32 v8, -v8, v38, v11
	v_div_fmas_f32 v117, v8, v10, v38
	v_mul_f32_e32 v8, 0xbfb8aa3b, v120
	v_exp_f32_e32 v8, v8
	s_nop 0
	v_pk_add_f32 v[102:103], v[8:9], 1.0 op_sel_hi:[1,0]
	s_nop 0
	v_div_scale_f32 v8, s[0:1], v103, v103, v121
	v_rcp_f32_e32 v9, v8
	s_nop 0
	v_fma_f32 v10, -v8, v9, 1.0
	v_fmac_f32_e32 v9, v10, v9
	v_div_scale_f32 v10, vcc, v121, v103, v121
	v_mul_f32_e32 v11, v10, v9
	v_fma_f32 v38, -v8, v11, v10
	v_fmac_f32_e32 v11, v38, v9
	v_fma_f32 v8, -v8, v11, v10
	v_div_fmas_f32 v122, v8, v9, v11
	v_div_scale_f32 v8, s[0:1], v102, v102, v120
	v_rcp_f32_e32 v9, v8
	s_nop 0
	v_fma_f32 v10, -v8, v9, 1.0
	v_fmac_f32_e32 v9, v10, v9
	v_div_scale_f32 v10, vcc, v120, v102, v120
	v_mul_f32_e32 v11, v10, v9
	v_fma_f32 v38, -v8, v11, v10
	v_fmac_f32_e32 v11, v38, v9
	v_fma_f32 v8, -v8, v11, v10
	v_div_fmas_f32 v123, v8, v9, v11
	v_lshl_add_u32 v8, v178, 2, s16
	ds_read_b128 v[8:11], v8
	v_lshl_add_u32 v38, v180, 2, s16
	ds_read_b128 v[38:41], v38
	s_waitcnt lgkmcnt(1)
	v_pk_mul_f32 v[8:9], v[8:9], v[34:35]
	v_div_fixup_f32 v35, v108, v43, v107
	v_div_fixup_f32 v34, v109, v42, v106
	v_pk_mul_f32 v[10:11], v[10:11], v[32:33]
	v_div_fixup_f32 v33, v118, v45, v113
	v_div_fixup_f32 v32, v119, v44, v112
	v_pk_mul_f32 v[8:9], v[34:35], v[8:9]
	v_pk_mul_f32 v[10:11], v[32:33], v[10:11]
	v_cvt_pk_bf16_f32 v8, v8, v9
	v_cvt_pk_bf16_f32 v9, v10, v11
	global_store_dwordx2 v[104:105], v[8:9], off
	s_waitcnt lgkmcnt(0)
	v_pk_mul_f32 v[28:29], v[38:39], v[28:29]
	v_pk_mul_f32 v[30:31], v[40:41], v[30:31]
	s_waitcnt vmcnt(10)
	v_mov_b32_e32 v8, v62
	v_mov_b32_e32 v9, v63
	v_lshlrev_b32_e32 v42, 16, v8
	v_and_b32_e32 v43, 0xffff0000, v8
	v_mul_f32_e32 v8, 0xbfb8aa3b, v42
	v_exp_f32_e32 v10, v8
	v_mul_f32_e32 v8, 0xbfb8aa3b, v43
	v_exp_f32_e32 v11, v8
	v_lshlrev_b32_e32 v104, 16, v9
	v_and_b32_e32 v105, 0xffff0000, v9
	v_mul_f32_e32 v9, 0xbfb8aa3b, v105
	v_pk_add_f32 v[10:11], v[10:11], 1.0 op_sel_hi:[1,0]
	v_exp_f32_e32 v9, v9
	v_div_scale_f32 v8, s[0:1], v11, v11, v43
	v_rcp_f32_e32 v32, v8
	s_nop 0
	v_fma_f32 v33, -v8, v32, 1.0
	v_fmac_f32_e32 v32, v33, v32
	v_div_scale_f32 v33, vcc, v43, v11, v43
	v_mul_f32_e32 v34, v33, v32
	v_fma_f32 v35, -v8, v34, v33
	v_fmac_f32_e32 v34, v35, v32
	v_fma_f32 v8, -v8, v34, v33
	v_div_fmas_f32 v44, v8, v32, v34
	v_div_scale_f32 v8, s[0:1], v10, v10, v42
	v_rcp_f32_e32 v32, v8
	v_div_fixup_f32 v11, v44, v11, v43
	v_fma_f32 v33, -v8, v32, 1.0
	v_fmac_f32_e32 v32, v33, v32
	v_div_scale_f32 v33, vcc, v42, v10, v42
	v_mul_f32_e32 v34, v33, v32
	v_fma_f32 v35, -v8, v34, v33
	v_fmac_f32_e32 v34, v35, v32
	v_fma_f32 v8, -v8, v34, v33
	v_div_fmas_f32 v45, v8, v32, v34
	v_mul_f32_e32 v8, 0xbfb8aa3b, v104
	v_exp_f32_e32 v8, v8
	v_div_fixup_f32 v10, v45, v10, v42
	v_pk_mul_f32 v[0:1], v[10:11], v[0:1]
	v_pk_mul_f32 v[10:11], v[24:25], v[18:19] op_sel_hi:[1,0]
	v_pk_add_f32 v[8:9], v[8:9], 1.0 op_sel_hi:[1,0]
	v_pk_mul_f32 v[2:3], v[2:3], v[10:11]
	v_div_scale_f32 v32, s[0:1], v9, v9, v105
	v_rcp_f32_e32 v33, v32
	v_cvt_pk_bf16_f32 v0, v0, v1
	v_fma_f32 v34, -v32, v33, 1.0
	v_fmac_f32_e32 v33, v34, v33
	v_div_scale_f32 v34, vcc, v105, v9, v105
	v_mul_f32_e32 v35, v34, v33
	v_fma_f32 v48, -v32, v35, v34
	v_fmac_f32_e32 v35, v48, v33
	v_fma_f32 v32, -v32, v35, v34
	v_div_fmas_f32 v106, v32, v33, v35
	v_div_scale_f32 v32, s[0:1], v8, v8, v104
	v_rcp_f32_e32 v33, v32
	v_div_fixup_f32 v9, v106, v9, v105
	v_fma_f32 v34, -v32, v33, 1.0
	v_fmac_f32_e32 v33, v34, v33
	v_div_scale_f32 v34, vcc, v104, v8, v104
	v_mul_f32_e32 v35, v34, v33
	v_fma_f32 v48, -v32, v35, v34
	v_fmac_f32_e32 v35, v48, v33
	v_fma_f32 v32, -v32, v35, v34
	v_div_fmas_f32 v107, v32, v33, v35
	v_div_fixup_f32 v35, v116, v47, v111
	v_div_fixup_f32 v34, v117, v46, v110
	v_pk_mul_f32 v[28:29], v[34:35], v[28:29]
	v_div_fixup_f32 v35, v122, v103, v121
	v_div_fixup_f32 v34, v123, v102, v120
	v_lshlrev_b32_e32 v48, 1, v180
	v_pk_mul_f32 v[30:31], v[34:35], v[30:31]
	v_lshl_add_u64 v[32:33], v[36:37], 0, v[48:49]
	v_cvt_pk_bf16_f32 v28, v28, v29
	v_cvt_pk_bf16_f32 v29, v30, v31
	global_store_dwordx2 v[32:33], v[28:29], off
	v_div_fixup_f32 v8, v107, v8, v104
	v_pk_mul_f32 v[2:3], v[8:9], v[2:3]
	s_waitcnt vmcnt(10)
	v_mov_b32_e32 v28, v64
	v_mov_b32_e32 v29, v65
	v_lshlrev_b32_e32 v32, 16, v28
	v_cvt_pk_bf16_f32 v1, v2, v3
	global_store_dwordx2 v[16:17], v[0:1], off offset:128
	v_and_b32_e32 v33, 0xffff0000, v28
	v_mul_f32_e32 v28, 0xbfb8aa3b, v32
	v_exp_f32_e32 v30, v28
	v_mul_f32_e32 v28, 0xbfb8aa3b, v33
	v_exp_f32_e32 v31, v28
	s_waitcnt vmcnt(10)
	v_mov_b32_e32 v0, v66
	v_mov_b32_e32 v1, v67
	v_lshlrev_b32_e32 v44, 16, v1
	v_pk_add_f32 v[30:31], v[30:31], 1.0 op_sel_hi:[1,0]
	v_and_b32_e32 v45, 0xffff0000, v1
	v_div_scale_f32 v28, s[0:1], v31, v31, v33
	v_rcp_f32_e32 v34, v28
	v_mul_f32_e32 v1, 0xbfb8aa3b, v45
	v_exp_f32_e32 v1, v1
	v_fma_f32 v35, -v28, v34, 1.0
	v_fmac_f32_e32 v34, v35, v34
	v_div_scale_f32 v35, vcc, v33, v31, v33
	v_mul_f32_e32 v36, v35, v34
	v_fma_f32 v37, -v28, v36, v35
	v_fmac_f32_e32 v36, v37, v34
	v_fma_f32 v28, -v28, v36, v35
	v_div_fmas_f32 v34, v28, v34, v36
	v_div_scale_f32 v28, s[0:1], v30, v30, v32
	v_rcp_f32_e32 v35, v28
	s_nop 0
	v_fma_f32 v36, -v28, v35, 1.0
	v_fmac_f32_e32 v35, v36, v35
	v_div_scale_f32 v36, vcc, v32, v30, v32
	v_mul_f32_e32 v37, v36, v35
	v_fma_f32 v38, -v28, v37, v36
	v_fmac_f32_e32 v37, v38, v35
	v_fma_f32 v28, -v28, v37, v36
	v_div_fmas_f32 v35, v28, v35, v37
	v_lshlrev_b32_e32 v36, 16, v29
	v_and_b32_e32 v37, 0xffff0000, v29
	v_mul_f32_e32 v28, 0xbfb8aa3b, v36
	v_mul_f32_e32 v29, 0xbfb8aa3b, v37
	v_exp_f32_e32 v28, v28
	v_exp_f32_e32 v29, v29
	s_nop 0
	v_pk_add_f32 v[28:29], v[28:29], 1.0 op_sel_hi:[1,0]
	s_nop 0
	v_div_scale_f32 v38, s[0:1], v29, v29, v37
	v_rcp_f32_e32 v39, v38
	s_nop 0
	v_fma_f32 v40, -v38, v39, 1.0
	v_fmac_f32_e32 v39, v40, v39
	v_div_scale_f32 v40, vcc, v37, v29, v37
	v_mul_f32_e32 v41, v40, v39
	v_fma_f32 v46, -v38, v41, v40
	v_fmac_f32_e32 v41, v46, v39
	v_fma_f32 v38, -v38, v41, v40
	v_div_fmas_f32 v38, v38, v39, v41
	v_div_scale_f32 v39, s[0:1], v28, v28, v36
	v_rcp_f32_e32 v40, v39
	s_nop 0
	v_fma_f32 v41, -v39, v40, 1.0
	v_fmac_f32_e32 v40, v41, v40
	v_div_scale_f32 v41, vcc, v36, v28, v36
	v_mul_f32_e32 v46, v41, v40
	v_fma_f32 v47, -v39, v46, v41
	v_fmac_f32_e32 v46, v47, v40
	v_fma_f32 v39, -v39, v46, v41
	v_div_fmas_f32 v39, v39, v40, v46
	v_lshlrev_b32_e32 v40, 16, v0
	v_and_b32_e32 v41, 0xffff0000, v0
	v_mul_f32_e32 v0, 0xbfb8aa3b, v40
	v_exp_f32_e32 v2, v0
	v_mul_f32_e32 v0, 0xbfb8aa3b, v41
	v_exp_f32_e32 v3, v0
	s_nop 0
	v_pk_add_f32 v[24:25], v[2:3], 1.0 op_sel_hi:[1,0]
	s_nop 0
	v_div_scale_f32 v0, s[0:1], v25, v25, v41
	v_rcp_f32_e32 v2, v0
	s_nop 0
	v_fma_f32 v3, -v0, v2, 1.0
	v_fmac_f32_e32 v2, v3, v2
	v_div_scale_f32 v3, vcc, v41, v25, v41
	v_mul_f32_e32 v8, v3, v2
	v_fma_f32 v9, -v0, v8, v3
	v_fmac_f32_e32 v8, v9, v2
	v_fma_f32 v0, -v0, v8, v3
	v_div_fmas_f32 v42, v0, v2, v8
	v_div_scale_f32 v0, s[0:1], v24, v24, v40
	v_rcp_f32_e32 v2, v0
	s_nop 0
	v_fma_f32 v3, -v0, v2, 1.0
	v_fmac_f32_e32 v2, v3, v2
	v_div_scale_f32 v3, vcc, v40, v24, v40
	v_mul_f32_e32 v8, v3, v2
	v_fma_f32 v9, -v0, v8, v3
	v_fmac_f32_e32 v8, v9, v2
	v_fma_f32 v0, -v0, v8, v3
	v_div_fmas_f32 v43, v0, v2, v8
	v_mul_f32_e32 v0, 0xbfb8aa3b, v44
	v_exp_f32_e32 v0, v0
	s_nop 0
	v_pk_add_f32 v[26:27], v[0:1], 1.0 op_sel_hi:[1,0]
	s_nop 0
	v_div_scale_f32 v0, s[0:1], v27, v27, v45
	v_rcp_f32_e32 v1, v0
	s_nop 0
	v_fma_f32 v2, -v0, v1, 1.0
	v_fmac_f32_e32 v1, v2, v1
	v_div_scale_f32 v2, vcc, v45, v27, v45
	v_mul_f32_e32 v3, v2, v1
	v_fma_f32 v8, -v0, v3, v2
	v_fmac_f32_e32 v3, v8, v1
	v_fma_f32 v0, -v0, v3, v2
	v_div_fmas_f32 v46, v0, v1, v3
	v_div_scale_f32 v0, s[0:1], v26, v26, v44
	v_rcp_f32_e32 v1, v0
	s_nop 0
	v_fma_f32 v2, -v0, v1, 1.0
	v_fmac_f32_e32 v1, v2, v1
	v_div_scale_f32 v2, vcc, v44, v26, v44
	v_mul_f32_e32 v3, v2, v1
	v_fma_f32 v8, -v0, v3, v2
	v_fmac_f32_e32 v3, v8, v1
	v_fma_f32 v0, -v0, v3, v2
	v_div_fmas_f32 v47, v0, v1, v3
	ds_read_b128 v[0:3], v19 offset:288
	ds_read_b128 v[8:11], v19 offset:320
	s_waitcnt lgkmcnt(1)
	v_pk_mul_f32 v[0:1], v[0:1], v[22:23]
	v_div_fixup_f32 v23, v34, v31, v33
	v_div_fixup_f32 v22, v35, v30, v32
	v_pk_mul_f32 v[2:3], v[2:3], v[20:21]
	v_div_fixup_f32 v21, v38, v29, v37
	v_div_fixup_f32 v20, v39, v28, v36
	v_pk_mul_f32 v[0:1], v[22:23], v[0:1]
	v_pk_mul_f32 v[2:3], v[20:21], v[2:3]
	v_cvt_pk_bf16_f32 v0, v0, v1
	v_cvt_pk_bf16_f32 v1, v2, v3
	global_store_dwordx2 v[16:17], v[0:1], off offset:144
	s_waitcnt vmcnt(10)
	v_mov_b32_e32 v0, v68
	v_mov_b32_e32 v1, v69
	v_lshrrev_b32_e32 v124, 6, v224
	v_mul_u32_u24_e32 v124, 0x1400, v124
	v_and_b32_e32 v126, 63, v224
	v_lshl_add_u32 v124, v126, 4, v124
	v_add_u32_e32 v124, 0x21000, v124
	ds_read_b128 v[50:53], v124
	ds_read_b128 v[54:57], v124 offset:1024
	ds_read_b128 v[58:61], v124 offset:2048
	ds_read_b128 v[62:65], v124 offset:3072
	ds_read_b128 v[66:69], v124 offset:4096
	v_lshlrev_b32_e32 v19, 16, v0
	v_and_b32_e32 v20, 0xffff0000, v0
	v_mul_f32_e32 v0, 0xbfb8aa3b, v19
	v_exp_f32_e32 v2, v0
	v_mul_f32_e32 v0, 0xbfb8aa3b, v20
	v_exp_f32_e32 v3, v0
	v_pk_mul_f32 v[14:15], v[14:15], v[18:19] op_sel_hi:[1,0]
	v_pk_add_f32 v[2:3], v[2:3], 1.0 op_sel_hi:[1,0]
	s_nop 0
	v_div_scale_f32 v0, s[0:1], v3, v3, v20
	v_rcp_f32_e32 v21, v0
	s_waitcnt lgkmcnt(0)
	v_pk_mul_f32 v[8:9], v[8:9], v[14:15]
	v_div_fixup_f32 v15, v42, v25, v41
	v_div_fixup_f32 v14, v43, v24, v40
	v_fma_f32 v22, -v0, v21, 1.0
	v_fmac_f32_e32 v21, v22, v21
	v_div_scale_f32 v22, vcc, v20, v3, v20
	v_mul_f32_e32 v23, v22, v21
	v_fma_f32 v28, -v0, v23, v22
	v_fmac_f32_e32 v23, v28, v21
	v_fma_f32 v0, -v0, v23, v22
	v_div_fmas_f32 v21, v0, v21, v23
	v_div_scale_f32 v0, s[0:1], v2, v2, v19
	v_rcp_f32_e32 v22, v0
	v_pk_mul_f32 v[8:9], v[14:15], v[8:9]
	v_pk_mul_f32 v[14:15], v[100:101], v[18:19] op_sel_hi:[1,0]
	v_cvt_pk_bf16_f32 v8, v8, v9
	v_fma_f32 v23, -v0, v22, 1.0
	v_fmac_f32_e32 v22, v23, v22
	v_div_scale_f32 v23, vcc, v19, v2, v19
	v_mul_f32_e32 v28, v23, v22
	v_fma_f32 v29, -v0, v28, v23
	v_fmac_f32_e32 v28, v29, v22
	v_fma_f32 v0, -v0, v28, v23
	v_div_fmas_f32 v22, v0, v22, v28
	v_lshlrev_b32_e32 v23, 16, v1
	v_and_b32_e32 v28, 0xffff0000, v1
	v_mul_f32_e32 v0, 0xbfb8aa3b, v23
	v_mul_f32_e32 v1, 0xbfb8aa3b, v28
	v_exp_f32_e32 v0, v0
	v_exp_f32_e32 v1, v1
	v_pk_mul_f32 v[10:11], v[10:11], v[14:15]
	v_div_fixup_f32 v15, v46, v27, v45
	v_div_fixup_f32 v14, v47, v26, v44
	v_pk_add_f32 v[0:1], v[0:1], 1.0 op_sel_hi:[1,0]
	v_pk_mul_f32 v[10:11], v[14:15], v[10:11]
	v_div_scale_f32 v29, s[0:1], v1, v1, v28
	v_rcp_f32_e32 v30, v29
	v_cvt_pk_bf16_f32 v9, v10, v11
	global_store_dwordx2 v[16:17], v[8:9], off offset:160
	v_pk_mul_f32 v[8:9], v[98:99], v[18:19] op_sel_hi:[1,0]
	v_fma_f32 v31, -v29, v30, 1.0
	v_fmac_f32_e32 v30, v31, v30
	v_div_scale_f32 v31, vcc, v28, v1, v28
	v_mul_f32_e32 v32, v31, v30
	v_fma_f32 v33, -v29, v32, v31
	v_fmac_f32_e32 v32, v33, v30
	v_fma_f32 v29, -v29, v32, v31
	v_div_fmas_f32 v29, v29, v30, v32
	v_div_scale_f32 v30, s[0:1], v0, v0, v23
	v_rcp_f32_e32 v31, v30
	v_pk_mul_f32 v[4:5], v[4:5], v[8:9]
	v_div_fixup_f32 v3, v21, v3, v20
	v_div_fixup_f32 v2, v22, v2, v19
	v_fma_f32 v32, -v30, v31, 1.0
	v_fmac_f32_e32 v31, v32, v31
	v_div_scale_f32 v32, vcc, v23, v0, v23
	v_mul_f32_e32 v33, v32, v31
	v_fma_f32 v34, -v30, v33, v32
	v_fmac_f32_e32 v33, v34, v31
	v_fma_f32 v30, -v30, v33, v32
	v_div_fmas_f32 v30, v30, v31, v33
	v_pk_mul_f32 v[2:3], v[2:3], v[4:5]
	v_pk_mul_f32 v[4:5], v[12:13], v[18:19] op_sel_hi:[1,0]
	v_div_fixup_f32 v1, v29, v1, v28
	v_pk_mul_f32 v[4:5], v[6:7], v[4:5]
	v_div_fixup_f32 v0, v30, v0, v23
	v_pk_mul_f32 v[0:1], v[0:1], v[4:5]
	v_cvt_pk_bf16_f32 v2, v2, v3
	v_cvt_pk_bf16_f32 v3, v0, v1
	global_store_dwordx2 v[16:17], v[2:3], off offset:176
	s_branch .LBB0_855
